# dil unit remap (consecutive query blocks per workgroup, same XCD) + per-workgroup rotation of the pattern order so all three dilations stay mixed in time
# speedup vs baseline: 1.0007x; 1.0007x over previous
.LBB0_481:
	s_add_u32 s2, s74, s0
	s_addc_u32 s3, s75, s1
	global_load_dwordx4 v[2:5], v0, s[2:3] offset:16
	global_load_dwordx4 v[10:13], v0, s[2:3]
	s_add_u32 s2, s76, s0
	s_addc_u32 s3, s77, s1
	global_load_dwordx4 v[14:17], v0, s[2:3]
	global_load_dwordx4 v[18:21], v0, s[2:3] offset:16
	s_add_u32 s0, s0, 32
	s_addc_u32 s1, s1, 0
	s_cmpk_lg_i32 s0, 0x100
	s_waitcnt vmcnt(2)
	v_max3_f32 v1, v8, |v10|, |v11|
	v_max3_f32 v1, v1, |v12|, |v13|
	s_waitcnt vmcnt(1)
	v_max3_f32 v6, v9, |v14|, |v15|
	v_max3_f32 v1, v1, |v2|, |v3|
	v_max3_f32 v2, v6, |v16|, |v17|
	v_max3_f32 v8, v1, |v4|, |v5|
	s_waitcnt vmcnt(0)
	v_max3_f32 v1, v2, |v18|, |v19|
	v_max3_f32 v9, v1, |v20|, |v21|
	s_cbranch_scc1 .LBB0_481
	v_readlane_b32 s0, v254, 36
	v_readlane_b32 s1, v254, 37
	s_lshr_b32 s98, s0, 8
	s_and_b32 s99, s0, 0xff
	s_and_b32 s101, s99, 7
	s_lshr_b32 s99, s99, 3
	s_mul_i32 s0, s99, 171
	s_lshr_b32 s0, s0, 9
	s_mul_i32 s0, s0, 3
	s_sub_i32 s0, s99, s0
	s_lshl_b32 s0, s0, 1
	s_add_i32 s98, s98, s0
	s_cmp_ge_u32 s98, 6
	s_cbranch_scc0 .Ldg_nr_a
	s_add_i32 s98, s98, -6
.Ldg_nr_a:
	s_cmp_lt_u32 s98, 2
	s_cbranch_scc1 .Ldg_p0_a
	s_cmp_lt_u32 s98, 4
	s_cbranch_scc1 .Ldg_p1_a
	s_lshl_b32 s101, s101, 6
	s_lshl_b32 s99, s99, 1
	s_add_i32 s101, s101, s99
	s_add_i32 s101, s101, s98
	s_add_i32 s101, s101, -4
	s_mul_i32 s0, s101, 3
	s_add_i32 s0, s0, 2
	s_branch .Ldg_done_a

.LBB0_491:
	s_mov_b32 s0, s15
	s_add_i32 s15, s15, s20
	s_cmpk_gt_i32 s15, 0x5ff
	s_cselect_b64 s[2:3], -1, 0
	s_cmpk_lt_i32 s15, 0x600
	s_cselect_b32 s0, s15, s0
	s_lshr_b32 s98, s0, 8
	s_and_b32 s99, s0, 0xff
	s_and_b32 s101, s99, 7
	s_lshr_b32 s99, s99, 3
	s_mul_i32 s0, s99, 171
	s_lshr_b32 s0, s0, 9
	s_mul_i32 s0, s0, 3
	s_sub_i32 s0, s99, s0
	s_lshl_b32 s0, s0, 1
	s_add_i32 s98, s98, s0
	s_cmp_ge_u32 s98, 6
	s_cbranch_scc0 .Ldg_nr_b
	s_add_i32 s98, s98, -6
